# c17 + fused-LN exchange polls the 8 slots directly (epoch parity in the sign bit of M2, slots zeroed at kernel start) instead of count -> poll -> barrier -> slot loads
# speedup vs baseline: 1.0034x; 1.0011x over previous
; #define LAS __attribute__((address_space(3)))
; __global__ void __launch_bounds__(NTHR, 2) enc_fwd(Args args) {
;     ...
;     bf16* Wb = (bf16*)(ws + WS_W);
;     unsigned char* scr = ws + WS_SCR;
;     bf16* XB = (bf16*)(scr + S_XB); bf16* YB = (bf16*)(scr + S_YB); bf16* HB = (bf16*)(scr + S_HID);
;     LAS unsigned char* ring = F.lds;
;     if (RUN(0) && args.g_lo == 0 && args.l_lo == 0) { p_prologue(F, args.in, Wb, (float*)(ws + WS_SPT), (bf16*)(scr + S_XB0)); GRID_BAR(); }
;     for (int grp = args.g_lo; grp < args.g_hi; ++grp) {
;         float* X = args.out + (size_t)grp * TG * D;
;         const int L = grp < 2 ? 2048 : 8192;
;         const float* Xin0 = grp < 2 ? args.in[0] + (size_t)grp * TG * D : args.in[1] + (size_t)(grp - 2) * TG * D;
;         const bf16* XB0g = (const bf16*)(scr + S_XB0) + (size_t)grp * TG * D;
;         for (int layer = args.l_lo; layer < args.l_hi; ++layer) {
;             const int kind = layer % 3, jl = layer / 3;
;             int Kout = 2048; const bf16* Wout; const bf16* XA = layer == 0 ? XB0g : XB;
;             if (kind == 0) {
;                 bf16* GATE = (bf16*)(scr + S_RG_GATE); bf16* URAW = (bf16*)(scr + S_RG_URAW); bf16* LA = (bf16*)(scr + S_RG_LA); bf16* INP = (bf16*)(scr + S_RG_INP);
;                 float* HEND = (float*)(scr + S_RG_HEND); float* PROD = (float*)(scr + S_RG_PROD); float* HIN = (float*)(scr + S_RG_HIN);
;                 if (RUN(10)) REPEAT(1) { pg8::Gemm g{XA, Wb + W_RGIN + (size_t)jl * 4096 * 2048, 2048, 2048, 1}; pg8::StaticOrder S; S.init(TG, 4096, F.G, (int)blockIdx.x);
;                     pg8::EpiRgIn E{GATE, URAW}; pg8::gemm_phase<pg8::EpiRgIn>(ring, g, S, E, tpacc, TMODE()); GRID_BAR(); }
;                 if (RUN(11)) { p_rg_fused(F, URAW, L, args.in[3] + (size_t)jl * 4 * 2048, args.in[4] + (size_t)jl * 2048, Wb + W_RGGATE + (size_t)jl * 32 * 65536,
;                                           args.in[6] + (size_t)jl * 2 * 2048, args.in[8] + (size_t)jl * 2 * 2048, (const float*)(ws + WS_SPT) + (size_t)jl * 2 * 2048, LA, INP, HEND, PROD); GRID_BAR(); }
;                 if (RUN(14)) REPEAT(3) { p_rg_scan_b(F, HEND, PROD, HIN, L); GRID_BAR(); }
;                 if (RUN(15)) REPEAT(3) { p_rg_scan_c(F, LA, INP, HIN, GATE, YB); GRID_BAR(); }
;                 Wout = Wb + W_RGOUT + (size_t)jl * 2048 * 2048;
;             } else if (kind == 1) {
.LBB0_114:
	v_readlane_b32 s18, v250, 2
	v_readlane_b32 s19, v250, 3
	s_add_u32 s92, s18, 0x19300000
	s_addc_u32 s93, s19, 0
	s_add_u32 s38, s18, 0x1b300000
	s_addc_u32 s39, s19, 0
	s_add_u32 s52, s18, 0x1f300000
	s_addc_u32 s53, s19, 0
	s_add_u32 s0, s18, 0x37800000
	v_readlane_b32 s24, v250, 16
	v_writelane_b32 v251, s0, 7
	s_addc_u32 s0, s19, 0
	v_readlane_b32 s26, v250, 18
	v_readlane_b32 s27, v250, 19
	s_cmp_lt_i32 s26, s27
	v_writelane_b32 v251, s0, 8
	s_cselect_b64 s[0:1], -1, 0
	s_add_u32 s76, s18, 0x23300000
	s_addc_u32 s77, s19, 0
	s_add_u32 s36, s18, 0x29300000
	s_addc_u32 s37, s19, 0
	s_add_u32 s8, s18, 0x2d300000
	v_writelane_b32 v251, s0, 9
	s_addc_u32 s9, s19, 0
	v_readlane_b32 s25, v250, 17
	v_writelane_b32 v251, s1, 10
	s_add_u32 s0, s18, 0x2e300000
	v_writelane_b32 v251, s0, 11
	s_addc_u32 s0, s19, 0
	v_writelane_b32 v251, s0, 12
	s_add_u32 s0, s18, 0x2f300000
	s_addc_u32 s1, s19, 0
	s_add_u32 s62, s18, 0x2f700000
	v_writelane_b32 v251, s0, 13
	s_addc_u32 s63, s19, 0
	v_mov_b32_e32 v131, 0
	v_writelane_b32 v251, s1, 14
	s_add_u32 s0, s18, 0x2f800000
	s_addc_u32 s1, s19, 0
	v_writelane_b32 v251, s0, 15
	s_cmp_eq_u32 s2, 20
	v_mov_b32_e32 v230, 0x3ecc95a3
	v_writelane_b32 v251, s1, 16
	s_cselect_b64 s[0:1], -1, 0
	s_or_b64 s[0:1], s[94:95], s[0:1]
	s_add_u32 s4, s18, 0x3a00000
	s_addc_u32 s5, s19, 0
	v_writelane_b32 v251, s0, 17
	s_cmpk_lt_i32 s89, 0x500
	v_mov_b32_e32 v226, 0x3727c5ac
	v_writelane_b32 v251, s1, 18
	s_cselect_b64 s[0:1], -1, 0
	v_writelane_b32 v251, s0, 19
	s_ashr_i32 s25, s89, 31
	s_ashr_i32 s10, s3, 31
	v_writelane_b32 v251, s1, 20
	s_lshr_b32 s0, s25, 29
	s_add_i32 s1, s89, s0
	s_ashr_i32 s0, s1, 3
	s_and_b32 s1, s1, -8
	s_sub_i32 s1, s89, s1
	v_writelane_b32 v251, s10, 21
	s_add_u32 s10, s18, 0x4200
	s_addc_u32 s11, s19, 0
	v_writelane_b32 v251, s10, 22
	v_mov_b32_e32 v192, 0x3f317218
	v_mov_b32_e32 v227, 0x7f800000
	v_writelane_b32 v251, s11, 23
	s_add_u32 s10, s18, 0x4400
	s_addc_u32 s11, s19, 0
	v_writelane_b32 v251, s10, 24
	v_mov_b32_e32 v228, 0x7fc00000
	v_mov_b32_e32 v229, 0xff800000
	v_writelane_b32 v251, s11, 25
	s_add_u32 s10, s18, 0x4500
	s_addc_u32 s11, s19, 0
	v_writelane_b32 v251, s10, 26
	v_mov_b32_e32 v231, 0xff61b1e6
	v_mov_b64_e32 v[248:249], 0x200
	v_writelane_b32 v251, s11, 27
	s_add_u32 s10, s18, 0x4600
	s_addc_u32 s11, s19, 0
	v_writelane_b32 v251, s10, 28
	v_mov_b32_e32 v232, 0x50
	v_mov_b32_e32 v233, 0x60
	v_writelane_b32 v251, s11, 29
	s_add_u32 s10, s18, 0x4700
	s_addc_u32 s11, s19, 0
	v_writelane_b32 v251, s10, 30
	v_mov_b32_e32 v234, 0x70
	v_mov_b64_e32 v[198:199], 0x100
	v_writelane_b32 v251, s11, 31
	s_add_u32 s10, s18, 0x4800
	s_addc_u32 s11, s19, 0
	v_writelane_b32 v251, s10, 32
	v_mov_b64_e32 v[200:201], 0xff
	v_mov_b64_e32 v[202:203], 0x400
	v_writelane_b32 v251, s11, 33
	s_add_u32 s10, s18, 0x4900
	s_addc_u32 s11, s19, 0
	v_writelane_b32 v251, s10, 34
	v_mov_b64_e32 v[204:205], 0x3ff
	s_mov_b32 s97, 0x20000
	v_writelane_b32 v251, s11, 35
	s_add_u32 s10, s18, 0x4a00
	s_addc_u32 s11, s19, 0
	v_writelane_b32 v251, s10, 36
	s_mov_b32 s80, 0x10000
	s_movk_i32 s64, 0x4000
	v_writelane_b32 v251, s11, 37
	s_add_u32 s10, s18, 0x4b00
	s_addc_u32 s11, s19, 0
	v_writelane_b32 v251, s10, 38
	s_mov_b32 s33, 0x18000
	s_mov_b32 s49, 0x1a000
	v_writelane_b32 v251, s11, 39
	s_add_u32 s10, s18, 0x4c00
	s_addc_u32 s11, s19, 0
	v_writelane_b32 v251, s10, 40
	s_mov_b32 s50, 0x8000
	s_movk_i32 s82, 0x210
	v_writelane_b32 v251, s11, 41
	s_add_u32 s10, s18, 0x4d00
	s_addc_u32 s11, s19, 0
	v_writelane_b32 v251, s10, 42
	s_movk_i32 s83, 0x840
	s_movk_i32 s84, 0x3c0
	v_writelane_b32 v251, s11, 43
	s_add_u32 s10, s18, 0x4e00
	s_addc_u32 s11, s19, 0
	v_writelane_b32 v251, s10, 44
	s_mov_b64 s[58:59], 0x100
	s_nop 0
	v_writelane_b32 v251, s11, 45
	s_add_u32 s10, s18, 0x4f00
	s_addc_u32 s11, s19, 0
	v_writelane_b32 v251, s10, 46
	s_nop 1
	v_writelane_b32 v251, s11, 47
	s_add_u32 s10, s18, 0x5000
	s_addc_u32 s11, s19, 0
	v_writelane_b32 v251, s10, 48
	s_nop 1
	v_writelane_b32 v251, s11, 49
	s_add_u32 s10, s18, 0x5100
	s_addc_u32 s11, s19, 0
	v_writelane_b32 v251, s10, 50
	s_nop 1
	v_writelane_b32 v251, s11, 51
	s_add_u32 s10, s18, 0x5200
	s_addc_u32 s11, s19, 0
	v_writelane_b32 v251, s10, 52
	s_nop 1
	v_writelane_b32 v251, s11, 53
	s_add_u32 s10, s18, 0x5300
	s_addc_u32 s11, s19, 0
	v_writelane_b32 v251, s10, 54
	s_cmp_eq_u32 s68, 15
	s_nop 0
	v_writelane_b32 v251, s11, 55
	s_cselect_b64 s[10:11], -1, 0
	v_writelane_b32 v251, s10, 56
	s_cmp_eq_u32 s68, 14
	s_nop 0
	v_writelane_b32 v251, s11, 57
	s_cselect_b64 s[10:11], -1, 0
	v_writelane_b32 v251, s10, 58
	s_cmp_eq_u32 s68, 13
	s_nop 0
	v_writelane_b32 v251, s11, 59
	s_cselect_b64 s[10:11], -1, 0
	v_writelane_b32 v251, s10, 60
	s_cmp_eq_u32 s68, 12
	s_nop 0
	v_writelane_b32 v251, s11, 61
	s_cselect_b64 s[10:11], -1, 0
	v_writelane_b32 v251, s10, 62
	s_cmp_eq_u32 s68, 11
	s_nop 0
	v_writelane_b32 v251, s11, 63
	s_cselect_b64 s[10:11], -1, 0
	v_writelane_b32 v252, s10, 0
	s_cmp_eq_u32 s68, 10
	s_nop 0
	v_writelane_b32 v252, s11, 1
	s_cselect_b64 s[10:11], -1, 0
	v_writelane_b32 v252, s10, 2
	s_cmp_eq_u32 s68, 9
	s_nop 0
	v_writelane_b32 v252, s11, 3
	s_cselect_b64 s[10:11], -1, 0
	v_writelane_b32 v252, s10, 4
	s_cmp_eq_u32 s68, 8
	s_nop 0
	v_writelane_b32 v252, s11, 5
	s_cselect_b64 s[10:11], -1, 0
	v_writelane_b32 v252, s10, 6
	s_cmp_eq_u32 s68, 7
	s_nop 0
	v_writelane_b32 v252, s11, 7
	s_cselect_b64 s[10:11], -1, 0
	v_writelane_b32 v252, s10, 8
	s_cmp_eq_u32 s68, 6
	s_nop 0
	v_writelane_b32 v252, s11, 9
	s_cselect_b64 s[10:11], -1, 0
	v_writelane_b32 v252, s10, 10
	s_cmp_eq_u32 s68, 5
	s_nop 0
	v_writelane_b32 v252, s11, 11
	s_cselect_b64 s[10:11], -1, 0
; #define RUN(k) ((ph < 0 || ph == (k)) && (tph = (k), tp0 = (PROBE_TMASK ? __builtin_amdgcn_s_memrealtime() : 0ull), true))
; #define REPEAT(bit) _Pragma("unroll 1") for (int rep = 0; rep < NREP(bit); ++rep)
; #define GRID_BAR() do { if (ph < 0) xcd_barrier(bar); if (PROBE_TMASK && !PROBE_GPART && (((unsigned long long)PROBE_TMASK >> tph) & 1ull)) tpacc += __builtin_amdgcn_s_memrealtime() - tp0; } while (0)
; __global__ void __launch_bounds__(NTHR, 2) enc_fwd(Args args) {
;     ...
;             unsigned long long* xslot = (unsigned long long*)(ws + WS_XSLOT); unsigned* pcnt = (unsigned*)(ctl + CW_SEAM); unsigned* ptmo = (unsigned*)(ctl + CW_TMO);
;             const unsigned ep = (unsigned)((grp * DEPTH + layer) * 2);
;             if (RUN(40)) { pg8::Gemm g{YB, Wout, Kout, Kout, 0}; pg8::StaticOrder S; S.init(TG, D, F.G, (int)blockIdx.x);
;                 pg8::EpiResidLn<false> E{XA, nullptr, XB, args.in[25] + (size_t)layer * D, args.in[26] + (size_t)layer * D, ALPHA, xslot, pcnt, 64u * (ep + 1u), ptmo};
;                 pg8::gemm_phase<pg8::EpiResidLn<false>>(ring, g, S, E, tpacc, TMODE()); GRID_BAR(); }
;             if (RUN(42)) REPEAT(6) { pg8::Gemm g{XB, Wb + W_UP + (size_t)layer * 8192 * 2048, 2048, 2048, 1}; pg8::StaticOrder S; S.init(TG, HID, F.G, (int)blockIdx.x, WGM_UP);
;                 pg8::EpiRelu2 E{HB, HID}; pg8::gemm_phase<pg8::EpiRelu2>(ring, g, S, E, tpacc, TMODE()); GRID_BAR(); }
;             if (RUN(43)) { pg8::Gemm g{HB, Wb + W_DOWN + (size_t)layer * 2048 * 8192, 8192, 8192, 1}; pg8::StaticOrder S; S.init(TG, D, F.G, (int)blockIdx.x, WGM_DOWN);
;                 if (layer == DEPTH - 1) { pg8::EpiResidLn<true> E{XB, X, nullptr, args.in[27] + (size_t)layer * D, args.in[28] + (size_t)layer * D, ALPHA, xslot, pcnt, 64u * (ep + 2u), ptmo};
	v_writelane_b32 v252, s10, 12
	s_cmp_eq_u32 s68, 4
	s_nop 0
	v_writelane_b32 v252, s11, 13
	s_cselect_b64 s[10:11], -1, 0
	v_writelane_b32 v252, s10, 14
	s_cmp_eq_u32 s68, 3
	s_nop 0
	v_writelane_b32 v252, s11, 15
	s_cselect_b64 s[10:11], -1, 0
	v_writelane_b32 v252, s10, 16
	s_cmp_eq_u32 s68, 2
	s_nop 0
	v_writelane_b32 v252, s11, 17
	s_cselect_b64 s[10:11], -1, 0
	v_writelane_b32 v252, s10, 18
	s_cmp_eq_u32 s68, 1
	s_nop 0
	v_writelane_b32 v252, s11, 19
	s_cselect_b64 s[10:11], -1, 0
	v_writelane_b32 v252, s10, 20
	s_cmp_eq_u32 s68, 0
	s_nop 0
	v_writelane_b32 v252, s11, 21
	s_cselect_b64 s[10:11], -1, 0
	v_writelane_b32 v252, s10, 22
	s_nop 1
	v_writelane_b32 v252, s11, 23
	s_lshl_b32 s10, s68, 8
	s_add_u32 s6, s6, s10
	s_addc_u32 s7, s7, 0
	s_add_u32 s10, s6, 0x1400
	s_addc_u32 s11, s7, 0
	v_writelane_b32 v252, s10, 24
	s_add_u32 s6, s6, 0x2400
	s_addc_u32 s7, s7, 0
	v_writelane_b32 v252, s11, 25
	v_writelane_b32 v252, s6, 26
	s_nop 1
	v_writelane_b32 v252, s7, 27
	s_add_u32 s6, s18, 0x7400
	s_addc_u32 s7, s19, 0
	v_writelane_b32 v252, s6, 28
	s_nop 1
	v_writelane_b32 v252, s7, 29
	s_add_u32 s6, s18, 0x7500
	s_addc_u32 s7, s19, 0
	v_writelane_b32 v252, s6, 30
	s_cmp_eq_u32 s2, 21
	s_nop 0
	v_writelane_b32 v252, s7, 31
	s_cselect_b64 s[6:7], -1, 0
	s_or_b64 s[6:7], s[94:95], s[6:7]
	v_writelane_b32 v252, s6, 32
	s_cmpk_lt_i32 s89, 0x100
	s_nop 0
	v_writelane_b32 v252, s7, 33
	s_cselect_b64 s[6:7], -1, 0
	v_writelane_b32 v252, s6, 34
	s_cmpk_lt_i32 s89, 0x600
	s_nop 0
	v_writelane_b32 v252, s7, 35
	s_cselect_b64 s[6:7], -1, 0
	v_writelane_b32 v252, s6, 36
	s_cmp_eq_u32 s2, 22
	s_nop 0
	v_writelane_b32 v252, s7, 37
	s_cselect_b64 s[6:7], -1, 0
	s_or_b64 s[6:7], s[94:95], s[6:7]
	v_writelane_b32 v252, s6, 38
	s_cmpk_lt_i32 s89, 0x200
	s_nop 0
	v_writelane_b32 v252, s7, 39
	s_cselect_b64 s[6:7], -1, 0
	v_writelane_b32 v252, s6, 40
	s_cmp_eq_u32 s2, 23
	s_nop 0
	v_writelane_b32 v252, s7, 41
	s_cselect_b64 s[6:7], -1, 0
	s_or_b64 s[6:7], s[94:95], s[6:7]
	v_writelane_b32 v252, s6, 42
	s_nop 1
	v_writelane_b32 v252, s7, 43
	s_lshl_b32 s6, s3, 9
	s_cmp_eq_u32 s2, 24
	v_writelane_b32 v252, s6, 44
	s_cselect_b64 s[6:7], -1, 0
	s_or_b64 s[6:7], s[94:95], s[6:7]
	v_writelane_b32 v252, s6, 45
	s_nop 1
	v_writelane_b32 v252, s7, 46
	s_add_u32 s6, s18, 0x6300000
	s_addc_u32 s7, s19, 0
	s_add_u32 s12, s18, 0x21300000
	s_addc_u32 s13, s19, 0
	s_add_u32 s26, s18, 0x25300000
	v_writelane_b32 v252, s6, 47
	s_addc_u32 s27, s19, 0
	s_nop 0
	v_writelane_b32 v252, s7, 48
	s_add_u32 s6, s18, 0x2d500000
	s_addc_u32 s7, s19, 0
	s_add_u32 s10, s18, 0x2d700000
	v_writelane_b32 v252, s10, 49
	s_addc_u32 s10, s19, 0
	s_cmp_eq_u32 s2, 10
	v_writelane_b32 v252, s10, 50
	s_cselect_b64 s[10:11], -1, 0
	s_or_b64 s[10:11], s[94:95], s[10:11]
	s_lshl_b32 s14, s1, 6
	v_writelane_b32 v252, s10, 51
	s_cmp_eq_u32 s2, 11
	s_nop 0
	v_writelane_b32 v252, s11, 52
	s_cselect_b64 s[10:11], -1, 0
	s_or_b64 s[10:11], s[94:95], s[10:11]
	v_writelane_b32 v252, s10, 53
	s_nop 1
	v_writelane_b32 v252, s11, 54
	s_add_u32 s10, s18, 0x2200000
	v_writelane_b32 v252, s10, 55
	s_addc_u32 s10, s19, 0
	v_writelane_b32 v252, s10, 56
	s_add_u32 s10, s18, 0x80000
	v_writelane_b32 v252, s10, 57
	s_addc_u32 s10, s19, 0
	s_cmp_eq_u32 s2, 14
	v_writelane_b32 v252, s10, 58
	s_cselect_b64 s[10:11], -1, 0
	s_or_b64 s[10:11], s[94:95], s[10:11]
	v_writelane_b32 v252, s10, 59
	s_cmp_eq_u32 s2, 15
	s_nop 0
	v_writelane_b32 v252, s11, 60
	s_cselect_b64 s[10:11], -1, 0
	s_or_b64 s[10:11], s[94:95], s[10:11]
	s_add_u32 s40, s18, 0x27300000
	s_addc_u32 s41, s19, 0
	s_add_u32 s42, s18, 0x2b300000
	v_writelane_b32 v252, s10, 61
	s_addc_u32 s43, s19, 0
	s_nop 0
	v_writelane_b32 v252, s11, 62
	s_add_u32 s10, s18, 0x2a00000
	v_writelane_b32 v252, s10, 63
	s_addc_u32 s10, s19, 0
	s_cmp_eq_u32 s2, 30
	v_writelane_b32 v253, s10, 0
	s_cselect_b64 s[10:11], -1, 0
	s_or_b64 s[10:11], s[94:95], s[10:11]
	s_add_u32 s22, s18, 0x7300000
	s_addc_u32 s23, s19, 0
	v_writelane_b32 v253, s10, 1
	s_cmpk_lt_i32 s89, 0x300
	s_nop 0
	v_writelane_b32 v253, s11, 2
	s_cselect_b64 s[10:11], -1, 0
	v_writelane_b32 v253, s10, 3
	s_cmp_eq_u32 s2, 31
	s_nop 0
	v_writelane_b32 v253, s11, 4
	s_cselect_b64 s[10:11], -1, 0
	s_or_b64 s[10:11], s[94:95], s[10:11]
	v_writelane_b32 v253, s10, 5
	s_nop 1
	v_writelane_b32 v253, s11, 6
	s_add_u32 s10, s18, 0x8b00000
	s_addc_u32 s11, s19, 0
	v_writelane_b32 v253, s10, 7
	s_nop 1
	v_writelane_b32 v253, s11, 8
	s_add_u32 s10, s18, 0x100000
	s_addc_u32 s11, s19, 0
	v_writelane_b32 v253, s10, 9
	s_nop 1
	v_writelane_b32 v253, s11, 10
	v_mov_b32_e32 v1, s89
	v_lshlrev_b32_e32 v1, 11, v1
	v_lshl_add_u32 v1, v0, 2, v1
	global_store_dword v1, v131, s[10:11] sc1
	s_add_u32 s10, s18, 0x10000
	v_writelane_b32 v253, s10, 11
	s_addc_u32 s10, s19, 0
	s_cmp_eq_u32 s2, 40
	v_writelane_b32 v253, s10, 12
	s_cselect_b64 s[10:11], -1, 0
	s_or_b64 s[10:11], s[94:95], s[10:11]
	s_lshl_b32 s15, s1, 5
	v_writelane_b32 v253, s10, 13
	s_cmp_eq_u32 s2, 42
	s_nop 0
	v_writelane_b32 v253, s11, 14
	s_cselect_b64 s[10:11], -1, 0
	s_or_b64 s[10:11], s[94:95], s[10:11]
	v_writelane_b32 v253, s10, 15
	s_nop 1
	v_writelane_b32 v253, s11, 16
	s_add_u32 s10, s18, 0x9300000
	v_writelane_b32 v253, s10, 17
	s_addc_u32 s10, s19, 0
	s_cmpk_lt_i32 s89, 0x400
	v_writelane_b32 v253, s10, 18
	s_cselect_b64 s[10:11], -1, 0
	s_lshl_b32 s16, s1, 7
	v_writelane_b32 v253, s10, 19
	s_cmp_eq_u32 s2, 43
	s_nop 0
	v_writelane_b32 v253, s11, 20
	s_cselect_b64 s[10:11], -1, 0
	s_or_b64 s[10:11], s[94:95], s[10:11]
	v_writelane_b32 v253, s10, 21
	s_add_u32 s2, s18, 0x11300000
	s_nop 0
	v_writelane_b32 v253, s11, 22
	v_writelane_b32 v253, s2, 23
	s_addc_u32 s2, s19, 0
;     __host__ __device__ bool next(int i, Unit& u) const {
;         const long L = (long)i * G + c; if (L >= nwg) return false;
;         int wgid = (int)L; { const int q = nwg / NXCD, r = nwg % NXCD, xcd = wgid % NXCD, off = wgid / NXCD; wgid = (xcd < r ? xcd * (q + 1) : r * (q + 1) + (xcd - r) * q) + off; }
;         const int nig = wgm * nN, gid = wgid / nig, fm = gid * wgm, gsz = (nM - fm) < wgm ? (nM - fm) : wgm;
;         u.pm = fm + ((wgid % nig) % gsz); u.pn = (wgid % nig) / gsz; return true;
	s_cmp_lt_i32 s1, 0
	s_mul_i32 s10, s1, 33
	s_cselect_b32 s17, s10, s15
	s_mul_i32 s10, s1, 0x81
	s_cselect_b32 s18, s10, s16
	s_movk_i32 s10, 0xa1
	s_cselect_b32 s10, s10, 0xa0
	v_writelane_b32 v253, s2, 24
	s_mul_i32 s2, s1, 0x41
	s_mul_i32 s10, s1, s10
	s_movk_i32 s11, 0x61
	s_cselect_b32 s2, s2, s14
	s_cselect_b32 s11, s11, 0x60
	s_add_i32 s10, s10, s0
	s_mul_hi_i32 s14, s10, 0x66666667
	s_lshr_b32 s15, s14, 31
	s_ashr_i32 s14, s14, 6
	s_add_i32 s14, s14, s15
	s_mul_i32 s15, s14, 0xa0
	s_sub_i32 s10, s10, s15
	s_bfe_u32 s15, s10, 0x2001d
	s_add_i32 s15, s10, s15
	s_and_b32 s16, s15, 0xfffc
	s_add_i32 s2, s2, s0
	s_sub_i32 s10, s10, s16
	s_ashr_i32 s16, s2, 31
	s_lshr_b32 s16, s16, 26
	s_add_i32 s16, s2, s16
	s_and_b32 s19, s16, 0xffc0
	s_sub_i32 s2, s2, s19
	s_bfe_i32 s19, s2, 0x80000
	s_bfe_u32 s19, s19, 0x2000d
	s_mul_i32 s1, s1, s11
	s_add_i32 s19, s2, s19
	s_add_i32 s1, s1, s0
	s_and_b32 s20, s19, 0xfc
	s_mul_hi_i32 s11, s1, 0x2aaaaaab
	s_sub_i32 s2, s2, s20
	s_lshr_b32 s20, s11, 31
	s_ashr_i32 s11, s11, 4
	s_add_i32 s11, s11, s20
	s_mul_i32 s20, s11, 0x60
	s_sub_i32 s1, s1, s20
	s_bfe_i32 s20, s1, 0x80000
	s_bfe_u32 s20, s20, 0x2000d
	s_lshl_b32 s14, s14, 2
	s_sext_i32_i16 s10, s10
	s_add_i32 s20, s1, s20
	s_add_i32 s28, s14, s10
	s_ashr_i32 s10, s16, 6
	s_and_b32 s21, s20, 0xfc
	s_lshl_b32 s10, s10, 2
	s_sext_i32_i8 s2, s2
	s_sub_i32 s1, s1, s21
	s_add_i32 s30, s10, s2
	s_bfe_i32 s10, s20, 0x80000
	s_lshl_b32 s2, s11, 2
	s_sext_i32_i16 s10, s10
	s_sext_i32_i8 s1, s1
	s_sext_i32_i16 s21, s15
	s_bfe_i32 s14, s19, 0x80000
	s_add_i32 s34, s2, s1
	s_ashr_i32 s1, s10, 2
	s_sext_i32_i16 s19, s14
	v_writelane_b32 v253, s1, 25
	s_ashr_i32 s1, s21, 2
	s_lshr_b32 s2, s10, 2
	v_writelane_b32 v253, s1, 26
	s_ashr_i32 s1, s19, 2
	s_bfe_i64 s[10:11], s[2:3], 0x100000
	v_writelane_b32 v253, s1, 27
	s_mov_b32 s2, s34
	s_ashr_i32 s35, s34, 31
	v_writelane_b32 v253, s2, 28
	s_lshl_b64 s[14:15], s[10:11], 20
	s_lshr_b32 s16, s21, 2
	s_lshr_b32 s10, s19, 2
	v_writelane_b32 v253, s3, 29
	s_lshl_b64 s[20:21], s[34:35], 20
	v_writelane_b32 v253, s20, 30
	s_add_u32 s14, s22, s14
	s_addc_u32 s15, s23, s15
	v_writelane_b32 v253, s21, 31
	v_writelane_b32 v253, s22, 32
	s_add_u32 s20, s14, 0x80000
	v_writelane_b32 v253, s23, 33
	s_addc_u32 s21, s15, 0
	v_writelane_b32 v253, s20, 34
	s_mov_b32 s35, 0xa000
	s_mov_b32 s34, 0x1c000
	v_writelane_b32 v253, s21, 35
	s_add_u32 s20, s14, 0x4000
	s_addc_u32 s21, s15, 0
	v_writelane_b32 v253, s20, 36
	s_nop 1
	v_writelane_b32 v253, s21, 37
	s_add_u32 s20, s14, 0x84000
	v_writelane_b32 v253, s14, 38
	s_addc_u32 s21, s15, 0
	s_add_i32 s1, s17, s0
	s_ashr_i32 s2, s1, 31
	s_lshr_b32 s2, s2, 27
	s_add_i32 s2, s1, s2
	s_and_b32 s11, s2, 0xffe0
	s_sub_i32 s1, s1, s11
	s_bfe_i32 s11, s1, 0x80000
	s_bfe_u32 s11, s11, 0x2000d
	s_add_i32 s11, s1, s11
	v_writelane_b32 v253, s15, 39
	s_and_b32 s14, s11, 0xfc
	s_add_i32 s0, s18, s0
	s_sub_i32 s1, s1, s14
	s_ashr_i32 s14, s0, 31
	s_lshr_b32 s14, s14, 25
	s_add_i32 s14, s0, s14
	s_and_b32 s15, s14, 0xff80
	s_sub_i32 s0, s0, s15
	s_bfe_i32 s15, s0, 0x80000
	s_bfe_u32 s15, s15, 0x2000d
	s_add_i32 s15, s0, s15
	s_and_b32 s17, s15, 0xfc
	s_sub_i32 s17, s0, s17
	s_ashr_i32 s0, s2, 5
	s_bfe_i32 s2, s11, 0x80000
	v_writelane_b32 v253, s20, 40
	s_lshl_b32 s0, s0, 2
	s_sext_i32_i16 s2, s2
	s_sext_i32_i8 s1, s1
	v_writelane_b32 v253, s21, 41
	s_add_i32 s18, s0, s1
	s_ashr_i32 s0, s2, 2
	v_writelane_b32 v253, s0, 42
	s_lshr_b32 s0, s2, 2
	s_bfe_i64 s[20:21], s[0:1], 0x100000
	s_ashr_i32 s0, s14, 7
	s_bfe_i32 s1, s15, 0x80000
	s_lshl_b32 s0, s0, 2
	s_sext_i32_i16 s1, s1
	s_sext_i32_i8 s2, s17
;     __host__ __device__ bool next(int i, Unit& u) const {
;         const long L = (long)i * G + c; if (L >= nwg) return false;
;         int wgid = (int)L; { const int q = nwg / NXCD, r = nwg % NXCD, xcd = wgid % NXCD, off = wgid / NXCD; wgid = (xcd < r ? xcd * (q + 1) : r * (q + 1) + (xcd - r) * q) + off; }
;         const int nig = wgm * nN, gid = wgid / nig, fm = gid * wgm, gsz = (nM - fm) < wgm ? (nM - fm) : wgm;
;         u.pm = fm + ((wgid % nig) % gsz); u.pn = (wgid % nig) / gsz; return true;
	s_add_i32 s14, s0, s2
	s_ashr_i32 s0, s1, 2
	v_writelane_b32 v253, s0, 43
	s_lshr_b32 s0, s1, 2
	s_bfe_i64 s[0:1], s[0:1], 0x100000
	s_lshl_b64 s[0:1], s[0:1], 20
	v_writelane_b32 v253, s0, 44
	s_ashr_i32 s15, s14, 31
	s_ashr_i32 s19, s18, 31
	v_writelane_b32 v253, s1, 45
	s_mov_b32 s0, s14
	v_writelane_b32 v253, s0, 46
	s_mov_b32 s2, s28
	s_nop 0
	v_writelane_b32 v253, s1, 47
	s_lshl_b64 s[0:1], s[14:15], 20
	s_add_u32 s0, s92, s0
	s_addc_u32 s1, s93, s1
	s_add_u32 s14, s0, 0x80000
	s_addc_u32 s15, s1, 0
	v_writelane_b32 v253, s14, 48
	s_nop 1
	v_writelane_b32 v253, s15, 49
	s_add_u32 s14, s0, 0x4000
	v_writelane_b32 v253, s0, 50
	s_addc_u32 s15, s1, 0
	s_nop 0
	v_writelane_b32 v253, s1, 51
	v_writelane_b32 v253, s14, 52
	s_mov_b32 s0, s18
	s_nop 0
	v_writelane_b32 v253, s15, 53
	v_writelane_b32 v253, s0, 54
	s_nop 1
	v_writelane_b32 v253, s1, 55
	s_lshl_b64 s[0:1], s[18:19], 22
	s_add_u32 s14, s52, s0
	s_mov_b32 s0, s20
	s_addc_u32 s15, s53, s1
	v_writelane_b32 v253, s0, 56
	s_nop 1
	v_writelane_b32 v253, s1, 57
	s_lshl_b64 s[0:1], s[20:21], 22
	v_writelane_b32 v253, s0, 58
	s_nop 1
	v_writelane_b32 v253, s1, 59
	s_add_u32 s0, s14, 0x200000
	s_addc_u32 s1, s15, 0
	v_writelane_b32 v253, s0, 60
	s_nop 1
	v_writelane_b32 v253, s1, 61
	s_add_u32 s0, s14, 0x4000
	v_writelane_b32 v253, s14, 62
	s_addc_u32 s1, s15, 0
	v_writelane_b32 v254, s0, 0
	s_ashr_i32 s29, s28, 31
	v_writelane_b32 v253, s15, 63
	v_writelane_b32 v254, s1, 1
	s_bfe_i64 s[0:1], s[16:17], 0x100000
	v_writelane_b32 v254, s2, 2
	s_lshl_b64 s[0:1], s[0:1], 20
	s_lshl_b64 s[14:15], s[28:29], 20
	v_writelane_b32 v254, s3, 3
	v_writelane_b32 v254, s14, 4
	s_add_u32 s0, s4, s0
	s_addc_u32 s1, s5, s1
	v_writelane_b32 v254, s15, 5
	v_writelane_b32 v254, s4, 6
	s_add_u32 s4, s0, 0x80000
	v_writelane_b32 v254, s5, 7
	s_addc_u32 s5, s1, 0
	v_writelane_b32 v254, s4, 8
	s_mov_b32 s14, 0x30000
	s_mov_b32 s15, 0x800000
	v_writelane_b32 v254, s5, 9
	s_add_u32 s4, s0, 0x4000
	s_addc_u32 s5, s1, 0
	v_writelane_b32 v254, s4, 10
	s_nop 1
	v_writelane_b32 v254, s5, 11
	s_add_u32 s4, s0, 0x84000
	v_writelane_b32 v254, s0, 12
	s_addc_u32 s5, s1, 0
	s_ashr_i32 s31, s30, 31
	v_writelane_b32 v254, s1, 13
	v_writelane_b32 v254, s4, 14
	s_bfe_i64 s[0:1], s[10:11], 0x100000
	s_lshl_b64 s[0:1], s[0:1], 20
	v_writelane_b32 v254, s5, 15
	v_writelane_b32 v254, s0, 16
	s_mov_b32 s11, 0
	s_mov_b64 s[4:5], 0x80
	v_writelane_b32 v254, s1, 17
	s_lshl_b32 s0, s89, 9
	v_writelane_b32 v254, s0, 18
	s_lshl_b32 s0, s3, 10
	v_writelane_b32 v254, s0, 19
	s_add_i32 s0, 0, 0x19800
	v_writelane_b32 v254, s0, 20
	v_cmp_eq_u32_e64 s[0:1], 0, v0
	s_nop 1
	v_writelane_b32 v254, s0, 21
	s_nop 1
	v_writelane_b32 v254, s1, 22
	s_mov_b32 s0, s30
	v_writelane_b32 v254, s0, 23
	s_nop 1
	v_writelane_b32 v254, s1, 24
	s_lshl_b64 s[0:1], s[30:31], 20
	v_writelane_b32 v254, s0, 25
	s_nop 1
	v_writelane_b32 v254, s1, 26
	s_mov_b32 s0, s24
	v_writelane_b32 v254, s0, 27
	s_nop 1
	v_writelane_b32 v254, s1, 28
	v_writelane_b32 v254, s92, 29
	s_nop 1
	v_writelane_b32 v254, s93, 30
	v_writelane_b32 v254, s38, 31
	s_nop 1
	v_writelane_b32 v254, s39, 32
	v_writelane_b32 v254, s76, 33
	s_nop 1
	v_writelane_b32 v254, s77, 34
	v_writelane_b32 v254, s36, 35
	s_nop 1
	v_writelane_b32 v254, s37, 36
	v_writelane_b32 v254, s25, 37
	v_writelane_b32 v254, s26, 38
	s_nop 1
	v_writelane_b32 v254, s27, 39
	v_writelane_b32 v254, s40, 40
	s_nop 1
	v_writelane_b32 v254, s41, 41
	v_writelane_b32 v254, s42, 42
	s_nop 1
	v_writelane_b32 v254, s43, 43
	v_writelane_b32 v254, s89, 44
	v_writelane_b32 v254, s94, 45
	s_nop 1
	v_writelane_b32 v254, s95, 46
	s_branch .LBB0_116

;     __device__ __forceinline__ void fused(AccT& acc, const Unit& u, int wr, int wc, int fr_in, int fq_in, LAS unsigned char* lds, int wid, int lane_in) const {
;     ...
;         const int col5 = u.pn * BM + wc * 32 + 8 * fq;
;         f32x4 gg[2][2], bv[2][2];
; #pragma unroll
;         for (int bj = 0; bj < 2; ++bj)
; #pragma unroll
;             for (int n = 0; n < 2; ++n) { gg[bj][n] = *(const f32x4*)(g + col5 + bj * HALF + n * 4); bv[bj][n] = *(const f32x4*)(b + col5 + bj * HALF + n * 4); }
;         asm volatile("s_waitcnt lgkmcnt(0)" ::: "memory"); __builtin_amdgcn_s_barrier(); asm volatile("" ::: "memory");
;         const int row = wid * 32 + (lane & 31);
;         if (lane < 32) {
;             const f32x2 a = P[row * 4 + 0], bb = P[row * 4 + 1], c = P[row * 4 + 2], d = P[row * 4 + 3];
;             const float mt = (a.x + bb.x + c.x + d.x) * 0.25f;
;             const float da = a.x - mt, db = bb.x - mt, dc = c.x - mt, dd = d.x - mt;
;             const float m2 = (a.y + bb.y) + (c.y + d.y) + 64.0f * ((da * da + db * db) + (dc * dc + dd * dd));
;             unsigned long long* slot = xbuf + ((size_t)(u.pm * BM + row) * 8 + u.pn);
;             __hip_atomic_store(slot, ((unsigned long long)__float_as_uint(m2) << 32) | __float_as_uint(mt), __ATOMIC_RELAXED, __HIP_MEMORY_SCOPE_AGENT);
;         }
;         asm volatile("s_waitcnt vmcnt(0)" ::: "memory");
;         if (lane == 0) __hip_atomic_fetch_add(cnt + 64 * u.pm, 1u, __ATOMIC_RELAXED, __HIP_MEMORY_SCOPE_AGENT);
.LBB0_1067:
	s_or_b64 exec, exec, s[18:19]
	v_readlane_b32 s0, v255, 4
	v_readlane_b32 s1, v255, 5
	v_readlane_b32 s36, v250, 8
	s_mov_b32 s18, s0
	s_ashr_i32 s19, s0, 31
	v_writelane_b32 v255, s0, 4
	v_readlane_b32 s38, v250, 10
	v_readlane_b32 s39, v250, 11
	v_writelane_b32 v255, s1, 5
	s_lshl_b64 s[0:1], s[18:19], 13
	s_mov_b64 s[18:19], s[38:39]
	v_readlane_b32 s40, v250, 12
	v_readlane_b32 s41, v250, 13
	s_add_u32 s18, s18, s0
	v_readlane_b32 s42, v250, 14
	v_readlane_b32 s43, v250, 15
	s_mov_b64 s[20:21], s[40:41]
	s_addc_u32 s19, s19, s1
	s_add_u32 s0, s20, s0
	v_ashrrev_i32_e32 v215, 31, v214
	s_addc_u32 s1, s21, s1
	s_waitcnt lgkmcnt(0)
	v_lshlrev_b64 v[22:23], 2, v[214:215]
	v_lshl_add_u64 v[38:39], s[18:19], 0, v[22:23]
	v_lshl_add_u64 v[144:145], s[0:1], 0, v[22:23]
	global_load_dwordx4 v[148:151], v[38:39], off offset:16
	global_load_dwordx4 v[156:159], v[38:39], off
	global_load_dwordx4 v[152:155], v[144:145], off offset:16
	global_load_dwordx4 v[160:163], v[144:145], off
	global_load_dwordx4 v[22:25], v[38:39], off offset:528
	global_load_dwordx4 v[140:143], v[38:39], off offset:512
	s_nop 0
	global_load_dwordx4 v[38:41], v[144:145], off offset:528
	s_nop 0
	global_load_dwordx4 v[144:147], v[144:145], off offset:512
	s_lshl_b32 s0, s46, 5
	s_waitcnt lgkmcnt(0)
	s_barrier
	v_and_or_b32 v1, v218, 31, s0
	v_add_u32_e32 v164, s24, v1
	v_cmp_gt_i32_e64 s[38:39], 32, v218
	v_ashrrev_i32_e32 v165, 31, v164
	v_readlane_b32 s37, v250, 9
	s_mov_b64 s[22:23], s[42:43]
	s_and_saveexec_b64 s[18:19], s[38:39]
	s_cbranch_execz .LBB0_1069
	v_lshl_add_u32 v170, v1, 5, 0
	ds_read_b128 v[166:169], v170
	ds_read_b128 v[170:173], v170 offset:16
	v_readlane_b32 s0, v253, 9
	v_readlane_b32 s1, v253, 10
	s_ashr_i32 s17, s16, 31
	s_waitcnt lgkmcnt(1)
	v_add_f32_e32 v174, v166, v168
	s_waitcnt lgkmcnt(0)
	v_add_f32_e32 v174, v174, v170
	v_add_f32_e32 v175, v174, v172
	v_fmamk_f32 v166, v175, 0xbe800000, v166
	v_fmac_f32_e32 v168, 0xbe800000, v175
	v_fmamk_f32 v170, v175, 0xbe800000, v170
	v_fmac_f32_e32 v172, 0xbe800000, v175
	v_mul_f32_e32 v177, v166, v166
	v_mul_f32_e32 v179, v168, v168
	v_mul_f32_e32 v181, v170, v170
	v_mul_f32_e32 v183, v172, v172
	v_mov_b32_e32 v176, v167
	v_mov_b32_e32 v178, v169
	v_mov_b32_e32 v180, v171
	v_mov_b32_e32 v182, v173
	v_pk_add_f32 v[166:167], v[176:177], v[178:179]
	v_pk_add_f32 v[168:169], v[180:181], v[182:183]
	v_mul_f32_e32 v174, 0x3e800000, v175
	v_pk_add_f32 v[166:167], v[166:167], v[168:169]
	v_lshlrev_b64 v[168:169], 6, v[164:165]
	v_fmac_f32_e32 v166, 0x42800000, v167
	v_lshl_add_u64 v[168:169], s[0:1], 0, v[168:169]
	v_lshl_add_u64 v[168:169], s[16:17], 3, v[168:169]
	v_mov_b32_e32 v175, v166
	v_or_b32_e32 v175, 0x80000000, v175
	global_store_dwordx2 v[168:169], v[174:175], off sc1
.LBB0_1069:
	s_or_b64 exec, exec, s[18:19]
	v_cmp_eq_u32_e64 s[40:41], 0, v218
	s_and_saveexec_b64 s[16:17], s[40:41]
	s_cbranch_execz .LBB0_1072
	s_mov_b64 s[18:19], exec
	v_mbcnt_lo_u32_b32 v166, s18, 0
	v_mbcnt_hi_u32_b32 v166, s19, v166
	v_cmp_eq_u32_e32 vcc, 0, v166
	s_and_b64 s[0:1], exec, vcc
	s_mov_b64 exec, s[0:1]
	s_cbranch_execz .LBB0_1072
	s_lshl_b32 s0, s48, 6
	s_ashr_i32 s1, s0, 31
	s_lshl_b64 s[0:1], s[0:1], 2
	v_readlane_b32 s20, v253, 11
	s_add_u32 s0, s20, s0
	v_readlane_b32 s20, v253, 12
	s_addc_u32 s1, s20, s1
	s_bcnt1_i32_b64 s18, s[18:19]
	v_mov_b32_e32 v166, s18
	global_atomic_add v131, v166, s[0:1]

;     __device__ __forceinline__ void fused(AccT& acc, const Unit& u, int wr, int wc, int fr_in, int fq_in, LAS unsigned char* lds, int wid, int lane_in) const {
;     ...
;         if (wid == 0) {
;             unsigned sp = 0;
;             while ((unsigned)__builtin_amdgcn_readfirstlane(__hip_atomic_load(cnt + 64 * u.pm, __ATOMIC_RELAXED, __HIP_MEMORY_SCOPE_AGENT)) < want) {
;                 __builtin_amdgcn_s_sleep(1);
;                 if ((++sp & 1023u) == 0u) { if (__builtin_amdgcn_readfirstlane(__hip_atomic_load(tmo, __ATOMIC_RELAXED, __HIP_MEMORY_SCOPE_AGENT)) != 0u) break;
;                     if (sp > (1u << 22)) { if (lane == 0) __hip_atomic_store(tmo, 1u, __ATOMIC_RELAXED, __HIP_MEMORY_SCOPE_AGENT); break; } } }
;             __builtin_amdgcn_fence(__ATOMIC_ACQUIRE, "agent");
;         }
;         asm volatile("s_waitcnt vmcnt(0) lgkmcnt(0)" ::: "memory"); __builtin_amdgcn_s_barrier(); asm volatile("" ::: "memory");
;         if (lane < 32) {
;             const unsigned long long* slot = xbuf + (size_t)(u.pm * BM + row) * 8; float mt[8], m2[8]; float ms = 0.f;
; #pragma unroll
;             for (int t = 0; t < 8; ++t) { const unsigned long long w = __hip_atomic_load(slot + t, __ATOMIC_RELAXED, __HIP_MEMORY_SCOPE_AGENT); mt[t] = __uint_as_float((unsigned)w); m2[t] = __uint_as_float((unsigned)(w >> 32)); ms += mt[t]; }
;             const float mean = ms * 0.125f; float q = 0.f;
; #pragma unroll
;             for (int t = 0; t < 8; ++t) { const float dm = mt[t] - mean; q += m2[t] + 256.0f * dm * dm; }
;             S[row] = (f32x2){mean, rsqrtf(q * (1.0f / 2048.0f) + LN_EPS)};
.LBB0_1087:
	s_and_saveexec_b64 s[16:17], s[38:39]
	s_cbranch_execz .LBB0_1089
	v_readlane_b32 s0, v253, 9
	v_lshlrev_b64 v[164:165], 6, v[164:165]
	v_readlane_b32 s1, v253, 10
	v_lshl_add_u32 v1, v1, 3, 0
	s_nop 0
	v_lshl_add_u64 v[164:165], s[0:1], 0, v[164:165]
	s_mov_b32 s20, 0
.Lxp0_retry:
	global_load_dwordx2 v[166:167], v[164:165], off sc1
	global_load_dwordx2 v[168:169], v[164:165], off offset:8 sc1
	global_load_dwordx2 v[170:171], v[164:165], off offset:16 sc1
	global_load_dwordx2 v[172:173], v[164:165], off offset:24 sc1
	global_load_dwordx2 v[174:175], v[164:165], off offset:32 sc1
	global_load_dwordx2 v[176:177], v[164:165], off offset:40 sc1
	global_load_dwordx2 v[178:179], v[164:165], off offset:48 sc1
	global_load_dwordx2 v[180:181], v[164:165], off offset:56 sc1
	s_waitcnt vmcnt(0)
	v_and_b32_e32 v182, v167, v169
	v_and_b32_e32 v182, v182, v171
	v_and_b32_e32 v182, v182, v173
	v_and_b32_e32 v182, v182, v175
	v_and_b32_e32 v182, v182, v177
	v_and_b32_e32 v182, v182, v179
	v_and_b32_e32 v182, v182, v181
	v_cmp_gt_i32_e32 vcc, 0, v182
	s_nop 4
	s_andn2_b64 vcc, exec, vcc
	s_cbranch_scc0 .Lxp0_done
	s_sleep 1
	s_add_i32 s20, s20, 1
	s_cmp_lt_u32 s20, 0x2000
	s_cbranch_scc1 .Lxp0_retry
.Lxp0_done:
	v_mov_b32_e32 v164, v180
	v_mov_b32_e32 v165, v181
	v_and_b32_e32 v167, 0x7fffffff, v167
	v_and_b32_e32 v169, 0x7fffffff, v169
	v_and_b32_e32 v171, 0x7fffffff, v171
	v_and_b32_e32 v173, 0x7fffffff, v173
	v_and_b32_e32 v175, 0x7fffffff, v175
	v_and_b32_e32 v177, 0x7fffffff, v177
	v_and_b32_e32 v179, 0x7fffffff, v179
	v_and_b32_e32 v165, 0x7fffffff, v165
	v_add_f32_e32 v180, 0, v166
	v_add_f32_e32 v180, v180, v168
	v_add_f32_e32 v180, v180, v170
	v_add_f32_e32 v180, v180, v172
	v_add_f32_e32 v180, v180, v174
	v_add_f32_e32 v180, v180, v176
	v_add_f32_e32 v180, v180, v178
	v_add_f32_e32 v181, v180, v164
	v_fmamk_f32 v166, v181, 0xbe000000, v166
	v_mul_f32_e32 v182, 0x43800000, v166
	v_fmac_f32_e32 v167, v166, v182
	v_add_f32_e32 v166, 0, v167
	v_fmamk_f32 v167, v181, 0xbe000000, v168
	v_mul_f32_e32 v168, 0x43800000, v167
	v_fmac_f32_e32 v169, v167, v168
	v_fmamk_f32 v167, v181, 0xbe000000, v170
	v_mul_f32_e32 v168, 0x43800000, v167
	v_fmac_f32_e32 v171, v167, v168
	v_fmamk_f32 v167, v181, 0xbe000000, v172
	v_mul_f32_e32 v168, 0x43800000, v167
	v_fmac_f32_e32 v173, v167, v168
	v_fmamk_f32 v167, v181, 0xbe000000, v174
	v_mul_f32_e32 v168, 0x43800000, v167
	v_add_f32_e32 v166, v169, v166
	v_fmac_f32_e32 v175, v167, v168
	v_fmamk_f32 v167, v181, 0xbe000000, v176
	v_add_f32_e32 v166, v171, v166
	v_mul_f32_e32 v168, 0x43800000, v167
	v_add_f32_e32 v166, v173, v166
	v_fmac_f32_e32 v177, v167, v168
	v_fmamk_f32 v167, v181, 0xbe000000, v178
	v_add_f32_e32 v166, v175, v166
	v_mul_f32_e32 v168, 0x43800000, v167
	v_fmamk_f32 v164, v181, 0xbe000000, v164
	v_add_f32_e32 v166, v177, v166
	v_fmac_f32_e32 v179, v167, v168
	v_mul_f32_e32 v167, 0x43800000, v164
	v_add_f32_e32 v166, v179, v166
	v_fmac_f32_e32 v165, v164, v167
	v_add_f32_e32 v164, v165, v166
	v_fmamk_f32 v164, v164, 0x3a000000, v226
	v_cmp_gt_f32_e32 vcc, s15, v164
	v_mul_f32_e32 v165, 0x4b800000, v164
	v_mul_f32_e32 v180, 0x3e000000, v181
	v_cndmask_b32_e32 v164, v164, v165, vcc
	v_rsq_f32_e32 v164, v164
	s_nop 0
	v_mul_f32_e32 v165, 0x45800000, v164
	v_cndmask_b32_e32 v181, v164, v165, vcc
	ds_write_b64 v1, v[180:181] offset:8192

;     __device__ __forceinline__ void fused(AccT& acc, const Unit& u, int wr, int wc, int fr_in, int fq_in, LAS unsigned char* lds, int wid, int lane_in) const {
;     ...
;         asm volatile("s_waitcnt vmcnt(0)" ::: "memory");
;         if (lane == 0) __hip_atomic_fetch_add(cnt + 64 * u.pm, 1u, __ATOMIC_RELAXED, __HIP_MEMORY_SCOPE_AGENT);
.LBB0_1251:
	s_or_b64 exec, exec, s[18:19]
	v_cmp_eq_u32_e64 s[40:41], 0, v218
	s_and_saveexec_b64 s[16:17], s[40:41]
	s_cbranch_execz .LBB0_1254
	s_mov_b64 s[18:19], exec
	v_mbcnt_lo_u32_b32 v166, s18, 0
	v_mbcnt_hi_u32_b32 v166, s19, v166
	v_cmp_eq_u32_e32 vcc, 0, v166
	s_and_b64 s[0:1], exec, vcc
	s_mov_b64 exec, s[0:1]
	s_cbranch_execz .LBB0_1254
	s_lshl_b32 s0, s56, 6
	s_ashr_i32 s1, s0, 31
	s_lshl_b64 s[0:1], s[0:1], 2
	v_readlane_b32 s20, v253, 11
	s_add_u32 s0, s20, s0
	v_readlane_b32 s20, v253, 12
	s_addc_u32 s1, s20, s1
	s_bcnt1_i32_b64 s18, s[18:19]
	v_mov_b32_e32 v166, s18
	global_atomic_add v131, v166, s[0:1]

;     __device__ __forceinline__ void fused(AccT& acc, const Unit& u, int wr, int wc, int fr_in, int fq_in, LAS unsigned char* lds, int wid, int lane_in) const {
;     ...
;         if (lane < 32) {
;             const unsigned long long* slot = xbuf + (size_t)(u.pm * BM + row) * 8; float mt[8], m2[8]; float ms = 0.f;
; #pragma unroll
;             for (int t = 0; t < 8; ++t) { const unsigned long long w = __hip_atomic_load(slot + t, __ATOMIC_RELAXED, __HIP_MEMORY_SCOPE_AGENT); mt[t] = __uint_as_float((unsigned)w); m2[t] = __uint_as_float((unsigned)(w >> 32)); ms += mt[t]; }
;             const float mean = ms * 0.125f; float q = 0.f;
; #pragma unroll
;             for (int t = 0; t < 8; ++t) { const float dm = mt[t] - mean; q += m2[t] + 256.0f * dm * dm; }
;             S[row] = (f32x2){mean, rsqrtf(q * (1.0f / 2048.0f) + LN_EPS)};
.Lxp1_retry:
	global_load_dwordx2 v[166:167], v[164:165], off sc1
	global_load_dwordx2 v[168:169], v[164:165], off offset:8 sc1
	global_load_dwordx2 v[170:171], v[164:165], off offset:16 sc1
	global_load_dwordx2 v[172:173], v[164:165], off offset:24 sc1
	global_load_dwordx2 v[174:175], v[164:165], off offset:32 sc1
	global_load_dwordx2 v[176:177], v[164:165], off offset:40 sc1
	global_load_dwordx2 v[178:179], v[164:165], off offset:48 sc1
	global_load_dwordx2 v[180:181], v[164:165], off offset:56 sc1
	s_waitcnt vmcnt(0)
	v_or_b32_e32 v182, v167, v169
	v_or_b32_e32 v182, v182, v171
	v_or_b32_e32 v182, v182, v173
	v_or_b32_e32 v182, v182, v175
	v_or_b32_e32 v182, v182, v177
	v_or_b32_e32 v182, v182, v179
	v_or_b32_e32 v182, v182, v181
	v_cmp_le_i32_e32 vcc, 0, v182
	s_nop 4
	s_andn2_b64 vcc, exec, vcc
	s_cbranch_scc0 .Lxp1_done
	s_sleep 1
	s_add_i32 s20, s20, 1
	s_cmp_lt_u32 s20, 0x2000
	s_cbranch_scc1 .Lxp1_retry
.Lxp1_done:
	v_mov_b32_e32 v164, v180
	v_mov_b32_e32 v165, v181
	v_add_f32_e32 v180, 0, v166
	v_add_f32_e32 v180, v180, v168
	v_add_f32_e32 v180, v180, v170
	v_add_f32_e32 v180, v180, v172
	v_add_f32_e32 v180, v180, v174
	v_add_f32_e32 v180, v180, v176
	v_add_f32_e32 v180, v180, v178
	v_add_f32_e32 v181, v180, v164
	v_fmamk_f32 v166, v181, 0xbe000000, v166
	v_mul_f32_e32 v182, 0x43800000, v166
	v_fmac_f32_e32 v167, v166, v182
	v_add_f32_e32 v166, 0, v167
	v_fmamk_f32 v167, v181, 0xbe000000, v168
	v_mul_f32_e32 v168, 0x43800000, v167
	v_fmac_f32_e32 v169, v167, v168
	v_fmamk_f32 v167, v181, 0xbe000000, v170
	v_mul_f32_e32 v168, 0x43800000, v167
	v_fmac_f32_e32 v171, v167, v168
	v_fmamk_f32 v167, v181, 0xbe000000, v172
	v_mul_f32_e32 v168, 0x43800000, v167
	v_fmac_f32_e32 v173, v167, v168
	v_fmamk_f32 v167, v181, 0xbe000000, v174
	v_mul_f32_e32 v168, 0x43800000, v167
	v_add_f32_e32 v166, v169, v166
	v_fmac_f32_e32 v175, v167, v168
	v_fmamk_f32 v167, v181, 0xbe000000, v176
	v_add_f32_e32 v166, v171, v166
	v_mul_f32_e32 v168, 0x43800000, v167
	v_add_f32_e32 v166, v173, v166
	v_fmac_f32_e32 v177, v167, v168
	v_fmamk_f32 v167, v181, 0xbe000000, v178
	v_add_f32_e32 v166, v175, v166
	v_mul_f32_e32 v168, 0x43800000, v167
	v_fmamk_f32 v164, v181, 0xbe000000, v164
	v_add_f32_e32 v166, v177, v166
	v_fmac_f32_e32 v179, v167, v168
	v_mul_f32_e32 v167, 0x43800000, v164
	v_add_f32_e32 v166, v179, v166
	v_fmac_f32_e32 v165, v164, v167
	v_add_f32_e32 v164, v165, v166
	v_fmamk_f32 v164, v164, 0x3a000000, v226
	v_cmp_gt_f32_e32 vcc, s15, v164
	v_mul_f32_e32 v165, 0x4b800000, v164
	v_mul_f32_e32 v180, 0x3e000000, v181
	v_cndmask_b32_e32 v164, v164, v165, vcc
	v_rsq_f32_e32 v164, v164
	s_nop 0
	v_mul_f32_e32 v165, 0x45800000, v164
	v_cndmask_b32_e32 v181, v164, v165, vcc
	ds_write_b64 v1, v[180:181] offset:8192
